# NSA compressed-branch K/V tile loads prefetched one iteration ahead
# speedup vs baseline: 1.0533x; 1.0007x over previous
.LBB0_182:
	s_lshl_b32 s5, s4, 3
	s_and_b32 s5, s5, 0x7f0
	s_lshr_b32 s6, s4, 7
	s_and_b32 s11, s4, 1
	s_or_b32 s4, s5, s6
	s_lshl_b32 s4, s4, 1
	v_mov_b32_e32 v60, v133
	s_and_b32 s9, s4, 0x1ffffe0
	s_sub_i32 s8, 0xfe0, s9
	v_and_b32_e32 v61, 31, v60
	s_and_b32 s12, s6, 14
	v_or_b32_e32 v126, s8, v61
	v_ashrrev_i32_e32 v23, 6, v60
	s_lshl_b32 s96, s12, 11
	v_ashrrev_i32_e32 v127, 31, v126
	v_lshl_add_u32 v4, s11, 2, v23
	v_lshl_add_u64 v[120:121], v[126:127], 0, s[96:97]
	v_lshlrev_b64 v[2:3], 10, v[120:121]
	v_lshlrev_b32_e32 v122, 6, v4
	v_bfe_u32 v22, v60, 5, 1
	v_lshl_add_u64 v[2:3], s[90:91], 0, v[2:3]
	v_ashrrev_i32_e32 v123, 31, v122
	v_lshl_add_u64 v[2:3], v[122:123], 1, v[2:3]
	v_lshlrev_b32_e32 v0, 4, v22
	v_lshl_add_u64 v[2:3], v[2:3], 0, v[0:1]
	v_readlane_b32 s4, v253, 19
	global_load_dwordx4 v[96:99], v[2:3], off
	global_load_dwordx4 v[100:103], v[2:3], off offset:32
	global_load_dwordx4 v[104:107], v[2:3], off offset:64
	global_load_dwordx4 v[108:111], v[2:3], off offset:96
	v_lshlrev_b64 v[2:3], 7, v[120:121]
	v_readlane_b32 s5, v253, 20
	v_lshl_add_u32 v4, v4, 1, v4
	v_ashrrev_i32_e32 v5, 31, v4
	v_lshl_add_u64 v[2:3], s[4:5], 0, v[2:3]
	v_lshl_add_u64 v[2:3], v[4:5], 2, v[2:3]
	global_load_dwordx3 v[116:118], v[2:3], off
	v_lshlrev_b32_e32 v124, 3, v22
	s_ashr_i32 s10, s8, 9
	s_cmp_gt_i32 s10, -1
	v_lshlrev_b32_e32 v25, 1, v124
	v_mul_u32_u24_e32 v0, 0x90, v61
	s_cselect_b64 s[4:5], -1, 0
	s_cmp_lt_i32 s10, 0
	v_lshlrev_b32_e32 v26, 4, v60
	s_waitcnt vmcnt(8)
	v_subrev_u32_e32 v50, 31, v126
	v_and_b32_e32 v24, 7, v60
	v_ashrrev_i32_e32 v62, 3, v60
	v_add_u32_e32 v63, v25, v0
	s_cbranch_scc1 .LBB0_186
	v_ashrrev_i32_e32 v2, 3, v60
	v_and_b32_e32 v0, 0x70, v26
	v_mad_u64_u32 v[18:19], s[6:7], v2, s37, v[0:1]
	s_add_i32 s6, s12, s11
	v_ashrrev_i32_e32 v3, 31, v2
	s_lshl_b32 s96, s6, 15
	v_lshlrev_b64 v[2:3], 7, v[2:3]
	v_lshl_add_u64 v[2:3], s[96:97], 0, v[2:3]
	v_readlane_b32 s6, v253, 21
	v_lshl_or_b32 v2, v24, 4, v2
	v_readlane_b32 s7, v253, 22
	s_mov_b64 s[14:15], s[66:67]
	v_lshl_or_b32 v0, v22, 6, v201
	v_lshl_add_u64 v[20:21], s[6:7], 0, v[2:3]
	s_add_i32 s6, s10, 1
	v_mov_b32_e32 v6, 0
	v_mov_b32_e32 v19, 0xf149f2ca
	global_load_dwordx4 v[230:233], v[20:21], off
	v_lshl_add_u64 v[20:21], v[20:21], 0, s[94:95]
.LBB0_184:
	s_waitcnt vmcnt(63) expcnt(7) lgkmcnt(15)
	s_barrier
	v_subrev_u32_e32 v28, 48, v0
	v_subrev_u32_e32 v29, 32, v0
	v_add_u32_e32 v30, -16, v0
	v_add_u32_e32 v7, 0xfffffe50, v0
	v_add_u32_e32 v8, 0xfffffe60, v0
	v_add_u32_e32 v9, 0xfffffe70, v0
	v_add_u32_e32 v10, 0xfffffe80, v0
	v_add_u32_e32 v11, 0xfffffed0, v0
	v_add_u32_e32 v12, 0xfffffee0, v0
	v_add_u32_e32 v13, 0xfffffef0, v0
	v_add_u32_e32 v14, 0xffffff00, v0
	v_add_u32_e32 v15, 0xffffff50, v0
	v_add_u32_e32 v16, 0xffffff60, v0
	v_add_u32_e32 v17, 0xffffff70, v0
	v_cmp_gt_i32_e64 s[62:63], v28, v50
	v_cmp_gt_i32_e64 s[64:65], v29, v50
	v_cmp_gt_i32_e64 s[66:67], v30, v50
	v_mov_b32_e32 v32, v6
	v_cmp_gt_i32_e64 s[38:39], v7, v50
	v_cmp_gt_i32_e64 s[40:41], v8, v50
	v_cmp_gt_i32_e64 s[42:43], v9, v50
	v_cmp_gt_i32_e64 s[44:45], v10, v50
	v_cmp_gt_i32_e64 s[46:47], v11, v50
	v_cmp_gt_i32_e64 s[48:49], v12, v50
	v_cmp_gt_i32_e64 s[50:51], v13, v50
	v_cmp_gt_i32_e64 s[52:53], v14, v50
	v_cmp_gt_i32_e64 s[54:55], v15, v50
	v_cmp_gt_i32_e64 s[56:57], v16, v50
	v_cmp_gt_i32_e64 s[58:59], v17, v50
	v_mov_b32_e32 v27, v19
	v_add_u32_e32 v19, 0xffffff80, v0
	v_cmp_gt_i32_e64 s[60:61], v19, v50
	v_cmp_gt_i32_e32 vcc, v0, v50
	s_add_i32 s6, s6, -1
	v_add_u32_e32 v0, 0x200, v0
	s_cmp_eq_u32 s6, 0
	s_waitcnt vmcnt(0)
	ds_write_b128 v18, v[230:233]
	s_cbranch_scc1 .Lnsa_c1_nopf
	global_load_dwordx4 v[230:233], v[20:21], off
	v_lshl_add_u64 v[20:21], v[20:21], 0, s[94:95]
.Lnsa_c1_nopf:
	s_waitcnt lgkmcnt(0)
	s_barrier
	ds_read_b128 v[2:5], v63
	ds_read_b128 v[28:31], v63 offset:32
	ds_read_b128 v[220:223], v63 offset:64
	ds_read_b128 v[224:227], v63 offset:96
	s_waitcnt lgkmcnt(3)
	v_mfma_f32_32x32x16_bf16 v[2:17], v[2:5], v[96:99], 0
	s_waitcnt lgkmcnt(2)
	v_mfma_f32_32x32x16_bf16 v[2:17], v[28:31], v[100:103], v[2:17]
	s_waitcnt lgkmcnt(1)
	v_mfma_f32_32x32x16_bf16 v[2:17], v[220:223], v[104:107], v[2:17]
	s_waitcnt lgkmcnt(0)
	v_mfma_f32_32x32x16_bf16 v[2:17], v[224:227], v[108:111], v[2:17]
	s_nop 11
	v_max_f32_e32 v19, v2, v2
	v_max_f32_e32 v19, 0xf149f2ca, v19
	v_cndmask_b32_e64 v28, v3, v202, s[40:41]
	v_cndmask_b32_e64 v29, v4, v202, s[42:43]
	v_cndmask_b32_e64 v19, v19, v202, s[38:39]
	v_cndmask_b32_e64 v30, v5, v202, s[44:45]
	v_cndmask_b32_e64 v31, v6, v202, s[46:47]
	v_max3_f32 v19, v19, v28, v29
	v_cndmask_b32_e64 v33, v7, v202, s[48:49]
	v_cndmask_b32_e64 v34, v8, v202, s[50:51]
	v_max3_f32 v19, v19, v30, v31
	v_cndmask_b32_e64 v35, v9, v202, s[52:53]
	v_cndmask_b32_e64 v36, v10, v202, s[54:55]
	v_max3_f32 v19, v19, v33, v34
	v_cndmask_b32_e64 v37, v11, v202, s[56:57]
	v_cndmask_b32_e64 v38, v12, v202, s[58:59]
	v_max3_f32 v19, v19, v35, v36
	v_cndmask_b32_e64 v39, v13, v202, s[60:61]
	v_cndmask_b32_e64 v40, v14, v202, s[62:63]
	v_max3_f32 v19, v19, v37, v38
	v_cndmask_b32_e64 v41, v15, v202, s[64:65]
	v_cndmask_b32_e64 v42, v16, v202, s[66:67]
	v_max3_f32 v19, v19, v39, v40
	v_cndmask_b32_e32 v43, v17, v202, vcc
	v_max3_f32 v19, v19, v41, v42
	v_max3_f32 v19, v27, v19, v43
	v_sub_f32_e32 v2, v2, v19
	v_sub_f32_e32 v3, v3, v19
	v_exp_f32_e32 v2, v2
	v_sub_f32_e32 v4, v4, v19
	v_exp_f32_e32 v3, v3
	v_sub_f32_e32 v5, v5, v19
	v_exp_f32_e32 v4, v4
	v_sub_f32_e32 v6, v6, v19
	v_exp_f32_e32 v5, v5
	v_sub_f32_e32 v7, v7, v19
	v_exp_f32_e32 v6, v6
	v_add_f32_e32 v2, 0, v2
	v_sub_f32_e32 v8, v8, v19
	v_exp_f32_e32 v7, v7
	v_cndmask_b32_e64 v3, v3, 0, s[40:41]
	v_cndmask_b32_e64 v2, v2, 0, s[38:39]
	v_sub_f32_e32 v9, v9, v19
	v_exp_f32_e32 v8, v8
	v_cndmask_b32_e64 v4, v4, 0, s[42:43]
	v_add_f32_e32 v2, v3, v2
	v_sub_f32_e32 v10, v10, v19
	v_exp_f32_e32 v9, v9
	v_cndmask_b32_e64 v5, v5, 0, s[44:45]
	v_add_f32_e32 v2, v4, v2
	v_sub_f32_e32 v11, v11, v19
	v_exp_f32_e32 v10, v10
	v_cndmask_b32_e64 v6, v6, 0, s[46:47]
	v_add_f32_e32 v2, v5, v2
	v_sub_f32_e32 v12, v12, v19
	v_exp_f32_e32 v11, v11
	v_cndmask_b32_e64 v7, v7, 0, s[48:49]
	v_add_f32_e32 v2, v6, v2
	v_sub_f32_e32 v13, v13, v19
	v_exp_f32_e32 v12, v12
	v_cndmask_b32_e64 v8, v8, 0, s[50:51]
	v_add_f32_e32 v2, v7, v2
	v_sub_f32_e32 v14, v14, v19
	v_exp_f32_e32 v13, v13
	v_cndmask_b32_e64 v9, v9, 0, s[52:53]
	v_add_f32_e32 v2, v8, v2
	v_sub_f32_e32 v15, v15, v19
	v_exp_f32_e32 v14, v14
	v_cndmask_b32_e64 v10, v10, 0, s[54:55]
	v_add_f32_e32 v2, v9, v2
	v_sub_f32_e32 v16, v16, v19
	v_exp_f32_e32 v15, v15
	v_cndmask_b32_e64 v11, v11, 0, s[56:57]
	v_add_f32_e32 v2, v10, v2
	v_sub_f32_e32 v17, v17, v19
	v_exp_f32_e32 v16, v16
	v_cndmask_b32_e64 v12, v12, 0, s[58:59]
	v_add_f32_e32 v2, v11, v2
	v_exp_f32_e32 v17, v17
	v_cndmask_b32_e64 v13, v13, 0, s[60:61]
	v_add_f32_e32 v2, v12, v2
	v_sub_f32_e32 v27, v27, v19
	v_cndmask_b32_e64 v14, v14, 0, s[62:63]
	v_add_f32_e32 v2, v13, v2
	v_exp_f32_e32 v27, v27
	v_cndmask_b32_e64 v15, v15, 0, s[64:65]
	v_add_f32_e32 v2, v14, v2
	v_cndmask_b32_e64 v16, v16, 0, s[66:67]
	v_add_f32_e32 v2, v15, v2
	v_cndmask_b32_e64 v17, v17, 0, vcc
	v_add_f32_e32 v2, v16, v2
	v_add_f32_e32 v6, v17, v2
	v_fmac_f32_e32 v6, v32, v27
	s_cbranch_scc0 .LBB0_184
	v_readlane_b32 s64, v253, 17
	v_readlane_b32 s65, v253, 18
	s_mov_b64 s[66:67], s[14:15]
	s_branch .LBB0_187

.LBB0_187:
	v_cmp_lt_i32_e32 vcc, v194, v193
	v_lshlrev_b32_e32 v4, 3, v60
	s_mov_b64 s[6:7], -1
	v_cndmask_b32_e32 v0, v192, v194, vcc
	v_lshlrev_b32_e32 v119, 2, v0
	ds_bpermute_b32 v2, v119, v19
	ds_bpermute_b32 v3, v119, v6
	s_and_b64 vcc, exec, s[4:5]
	v_and_b32_e32 v64, 56, v4
	s_cbranch_vccz .LBB0_191
	s_waitcnt lgkmcnt(1)
	v_max_f32_e32 v0, v2, v2
	v_max_f32_e32 v5, v19, v19
	v_max_f32_e32 v65, v5, v0
	v_sub_f32_e32 v0, v2, v65
	v_exp_f32_e32 v7, v0
	v_sub_f32_e32 v0, v19, v65
	v_exp_f32_e32 v2, v0
	v_ashrrev_i32_e32 v52, 3, v60
	v_readlane_b32 s6, v253, 23
	v_readlane_b32 s7, v253, 24
	s_waitcnt lgkmcnt(0)
	v_pk_mul_f32 v[2:3], v[6:7], v[2:3]
	s_waitcnt vmcnt(6)
	v_ashrrev_i32_e32 v53, 31, v52
	v_add_f32_e32 v0, v2, v3
	v_div_scale_f32 v2, s[4:5], v0, v0, 1.0
	v_rcp_f32_e32 v3, v2
	s_movk_i32 s4, 0x2400
	s_movk_i32 s5, 0x2080
	v_mov_b32_e32 v67, 0
	v_fma_f32 v5, -v2, v3, 1.0
	v_fmac_f32_e32 v3, v5, v3
	v_div_scale_f32 v5, vcc, 1.0, v0, 1.0
	v_mul_f32_e32 v6, v5, v3
	v_fma_f32 v7, -v2, v6, v5
	v_fmac_f32_e32 v6, v7, v3
	v_fma_f32 v2, -v2, v6, v5
	v_div_fmas_f32 v2, v2, v3, v6
	v_div_fixup_f32 v2, v2, v0, 1.0
	v_cmp_lt_f32_e32 vcc, 0, v0
	v_and_b32_e32 v0, 56, v4
	v_sub_u32_e32 v6, v25, v124
	v_cndmask_b32_e32 v54, 0, v2, vcc
	v_mul_lo_u32 v2, v52, s37
	v_lshl_add_u32 v66, v0, 1, v2
	v_ashrrev_i32_e32 v2, 2, v60
	v_ashrrev_i32_e32 v3, 31, v2
	v_lshlrev_b64 v[4:5], 9, v[2:3]
	v_mul_lo_u32 v2, v2, s37
	v_and_b32_e32 v3, 48, v26
	v_add3_u32 v68, v2, v3, s4
	v_mul_u32_u24_e32 v3, 0x48, v61
	v_lshlrev_b32_e32 v3, 1, v3
	v_add_u32_e32 v69, v6, v3
	v_lshl_or_b32 v70, v22, 3, v3
	v_mul_lo_u32 v3, v23, s5
	s_movk_i32 s5, 0x104
	v_mad_u32_u24 v3, v61, s5, v3
	s_add_i32 s5, s12, s11
	v_lshlrev_b32_e32 v2, 2, v22
	s_lshl_b32 s96, s5, 15
	v_add3_u32 v71, v3, v2, s36
	v_lshl_add_u64 v[2:3], s[96:97], 0, v[4:5]
	v_and_b32_e32 v4, 3, v60
	v_lshl_or_b32 v2, v4, 4, v2
	v_lshl_add_u64 v[56:57], s[6:7], 0, v[2:3]
	v_lshlrev_b64 v[2:3], 7, v[52:53]
	v_lshl_add_u64 v[2:3], s[96:97], 0, v[2:3]
	v_readlane_b32 s6, v253, 21
	v_lshl_or_b32 v2, v24, 4, v2
	v_readlane_b32 s7, v253, 22
	v_cmp_eq_u32_e32 vcc, 0, v22
	v_mov_b32_e32 v51, v50
	v_mov_b32_e32 v55, v54
	s_add_i32 s4, s10, 1
	v_lshlrev_b32_e32 v72, 6, v22
	v_lshl_add_u64 v[58:59], s[6:7], 0, v[2:3]
	v_mov_b32_e32 v2, 0
	v_mov_b32_e32 v3, v67
	v_mov_b32_e32 v4, v67
	v_mov_b32_e32 v5, v67
	v_mov_b32_e32 v6, v67
	v_mov_b32_e32 v7, v67
	v_mov_b32_e32 v8, v67
	v_mov_b32_e32 v9, v67
	v_mov_b32_e32 v10, v67
	v_mov_b32_e32 v11, v67
	v_mov_b32_e32 v12, v67
	v_mov_b32_e32 v13, v67
	v_mov_b32_e32 v14, v67
	v_mov_b32_e32 v15, v67
	v_mov_b32_e32 v16, v67
	v_mov_b32_e32 v17, v67
	v_mov_b32_e32 v18, 0
	v_mov_b32_e32 v19, v67
	v_mov_b32_e32 v20, v67
	v_mov_b32_e32 v21, v67
	v_mov_b32_e32 v22, v67
	v_mov_b32_e32 v23, v67
	v_mov_b32_e32 v24, v67
	v_mov_b32_e32 v25, v67
	v_mov_b32_e32 v26, v67
	v_mov_b32_e32 v27, v67
	v_mov_b32_e32 v28, v67
	v_mov_b32_e32 v29, v67
	v_mov_b32_e32 v30, v67
	v_mov_b32_e32 v31, v67
	v_mov_b32_e32 v32, v67
	v_mov_b32_e32 v33, v67
	global_load_dwordx4 v[230:233], v[58:59], off
	v_lshl_add_u64 v[58:59], v[58:59], 0, s[94:95]
	global_load_dwordx4 v[234:237], v[56:57], off
	v_lshl_add_u64 v[56:57], v[56:57], 0, 64
.LBB0_189:
	s_waitcnt vmcnt(63) expcnt(7) lgkmcnt(15)
	s_barrier
	v_add_u32_e32 v53, 16, v72
	v_cmp_le_i32_e64 s[38:39], v53, v51
	v_add_u32_e32 v78, 0x3000, v70
	s_add_i32 s4, s4, -1
	s_cmp_eq_u32 s4, 0
	s_waitcnt vmcnt(0)
	ds_write_b128 v66, v[230:233]
	ds_write_b128 v68, v[234:237]
	s_cbranch_scc1 .Lnsa_c2_nopf
	global_load_dwordx4 v[230:233], v[58:59], off
	v_lshl_add_u64 v[58:59], v[58:59], 0, s[94:95]
	global_load_dwordx4 v[234:237], v[56:57], off
	v_lshl_add_u64 v[56:57], v[56:57], 0, 64
.Lnsa_c2_nopf:
	s_waitcnt lgkmcnt(0)
	s_barrier
	ds_read_b128 v[34:37], v63
	ds_read_b128 v[74:77], v63 offset:32
	s_waitcnt lgkmcnt(1)
	v_mfma_f32_32x32x16_bf16 v[34:49], v[34:37], v[96:99], 0
	ds_read2_b64 v[78:81], v78 offset0:194 offset1:198
	s_waitcnt lgkmcnt(0)
	v_mov_b32_e32 v84, v78
	v_mov_b32_e32 v85, v79
	v_mfma_f32_32x32x16_bf16 v[34:49], v[74:77], v[100:103], v[34:49]
	ds_read_b128 v[74:77], v63 offset:64
	s_waitcnt lgkmcnt(0)
	v_mfma_f32_32x32x16_bf16 v[34:49], v[74:77], v[104:107], v[34:49]
	ds_read_b128 v[74:77], v63 offset:96
	s_waitcnt lgkmcnt(0)
	v_mfma_f32_32x32x16_bf16 v[34:49], v[74:77], v[108:111], v[34:49]
	v_add_u32_e32 v74, 0x3000, v69
	ds_read2_b64 v[74:77], v74 offset0:192 offset1:196
	s_waitcnt lgkmcnt(0)
	v_mov_b32_e32 v82, v74
	s_nop 7
	v_sub_f32_e32 v34, v34, v65
	v_sub_f32_e32 v35, v35, v65
	v_exp_f32_e32 v34, v34
	v_exp_f32_e32 v35, v35
	v_mov_b32_e32 v83, v75
	v_mov_b32_e32 v78, v76
	v_mov_b32_e32 v79, v77
	v_pk_mul_f32 v[34:35], v[54:55], v[34:35]
	s_nop 0
	v_cndmask_b32_e64 v53, 0, v35, s[38:39]
	v_cmp_le_i32_e64 s[38:39], v72, v50
	v_sub_f32_e32 v35, v37, v65
	v_exp_f32_e32 v35, v35
	v_cndmask_b32_e64 v73, 0, v34, s[38:39]
	v_sub_f32_e32 v34, v36, v65
	v_exp_f32_e32 v34, v34
	v_or_b32_e32 v36, 48, v72
	v_or_b32_e32 v37, 32, v72
	v_cmp_le_i32_e64 s[38:39], v36, v51
	v_pk_mul_f32 v[34:35], v[54:55], v[34:35]
	v_or_b32_e32 v36, 0x90, v72
	v_cndmask_b32_e64 v86, 0, v35, s[38:39]
	v_cmp_le_i32_e64 s[38:39], v37, v50
	v_sub_f32_e32 v35, v39, v65
	v_exp_f32_e32 v35, v35
	v_cndmask_b32_e64 v87, 0, v34, s[38:39]
	v_sub_f32_e32 v34, v38, v65
	v_exp_f32_e32 v34, v34
	v_or_b32_e32 v37, 0x80, v72
	v_cmp_le_i32_e64 s[38:39], v36, v51
	v_or_b32_e32 v36, 0xb0, v72
	v_pk_mul_f32 v[34:35], v[54:55], v[34:35]
	s_nop 0
	v_cndmask_b32_e64 v88, 0, v35, s[38:39]
	v_cmp_le_i32_e64 s[38:39], v37, v50
	v_sub_f32_e32 v35, v41, v65
	v_exp_f32_e32 v35, v35
	v_cndmask_b32_e64 v89, 0, v34, s[38:39]
	v_sub_f32_e32 v34, v40, v65
	v_exp_f32_e32 v34, v34
	v_or_b32_e32 v37, 0xa0, v72
	v_cmp_le_i32_e64 s[38:39], v36, v51
	v_or_b32_e32 v36, 0x110, v72
	v_pk_mul_f32 v[34:35], v[54:55], v[34:35]
	s_nop 0
	v_cndmask_b32_e64 v90, 0, v35, s[38:39]
	v_cmp_le_i32_e64 s[38:39], v37, v50
	v_sub_f32_e32 v35, v43, v65
	v_exp_f32_e32 v35, v35
	v_cndmask_b32_e64 v91, 0, v34, s[38:39]
	v_sub_f32_e32 v34, v42, v65
	v_exp_f32_e32 v34, v34
	v_or_b32_e32 v37, 0x100, v72
	v_cmp_le_i32_e64 s[38:39], v36, v51
	v_or_b32_e32 v36, 0x130, v72
	v_pk_mul_f32 v[34:35], v[54:55], v[34:35]
	v_mul_f32_e32 v74, 0.5, v90
	v_cndmask_b32_e64 v92, 0, v35, s[38:39]
	v_cmp_le_i32_e64 s[38:39], v37, v50
	v_sub_f32_e32 v35, v45, v65
	v_exp_f32_e32 v35, v35
	v_cndmask_b32_e64 v93, 0, v34, s[38:39]
	v_sub_f32_e32 v34, v44, v65
	v_exp_f32_e32 v34, v34
	v_or_b32_e32 v37, 0x120, v72
	v_cmp_le_i32_e64 s[38:39], v36, v51
	v_or_b32_e32 v36, 0x190, v72
	v_pk_mul_f32 v[34:35], v[54:55], v[34:35]
	ds_bpermute_b32 v74, v119, v74
	v_cndmask_b32_e64 v94, 0, v35, s[38:39]
	v_cmp_le_i32_e64 s[38:39], v37, v50
	v_sub_f32_e32 v35, v47, v65
	v_exp_f32_e32 v35, v35
	v_cndmask_b32_e64 v95, 0, v34, s[38:39]
	v_sub_f32_e32 v34, v46, v65
	v_exp_f32_e32 v34, v34
	v_or_b32_e32 v37, 0x180, v72
	v_cmp_le_i32_e64 s[38:39], v36, v51
	v_or_b32_e32 v36, 0x1b0, v72
	v_pk_mul_f32 v[34:35], v[54:55], v[34:35]
	v_add_u32_e32 v42, 0x2000, v69
	v_cndmask_b32_e64 v112, 0, v35, s[38:39]
	v_cmp_le_i32_e64 s[38:39], v37, v50
	v_sub_f32_e32 v35, v49, v65
	v_exp_f32_e32 v35, v35
	v_cndmask_b32_e64 v113, 0, v34, s[38:39]
	v_sub_f32_e32 v34, v48, v65
	v_exp_f32_e32 v34, v34
	v_or_b32_e32 v37, 0x1a0, v72
	v_cmp_le_i32_e64 s[38:39], v36, v51
	v_add_u32_e32 v46, 0x2000, v70
	v_pk_mul_f32 v[34:35], v[54:55], v[34:35]
	ds_read2_b64 v[42:45], v42 offset0:128 offset1:132
	v_cndmask_b32_e64 v114, 0, v35, s[38:39]
	v_cmp_le_i32_e64 s[38:39], v37, v50
	ds_read2_b64 v[46:49], v46 offset0:130 offset1:134
	v_cvt_pk_bf16_f32 v35, v87, v86
	v_cndmask_b32_e64 v115, 0, v34, s[38:39]
	v_cvt_pk_bf16_f32 v34, v73, v53
	v_add_f32_e32 v53, v73, v53
	v_mul_f32_e32 v73, 0.5, v86
	ds_bpermute_b32 v73, v119, v73
	v_add_f32_e32 v53, v87, v53
	v_fmac_f32_e32 v53, 0.5, v86
	s_waitcnt lgkmcnt(2)
	v_mov_b32_e32 v75, v43
	s_waitcnt lgkmcnt(1)
	v_mov_b32_e32 v76, v46
	s_waitcnt lgkmcnt(0)
	v_cndmask_b32_e32 v67, v73, v67, vcc
	v_add_f32_e32 v53, v53, v67
	v_add_f32_e32 v67, v89, v88
	v_add_f32_e32 v67, v91, v67
	v_fmac_f32_e32 v67, 0.5, v90
	v_cndmask_b32_e32 v73, v74, v73, vcc
	v_add_f32_e32 v67, v67, v73
	ds_write2_b32 v71, v53, v67 offset1:2
	v_mul_f32_e32 v67, 0.5, v94
	ds_bpermute_b32 v73, v119, v67
	v_add_f32_e32 v53, v93, v92
	v_add_f32_e32 v53, v95, v53
	v_fmac_f32_e32 v53, 0.5, v94
	v_mov_b32_e32 v77, v47
	s_waitcnt lgkmcnt(0)
	v_cndmask_b32_e32 v67, v73, v74, vcc
	v_add_f32_e32 v53, v53, v67
	v_add_f32_e32 v67, v113, v112
	v_add_f32_e32 v74, v115, v67
	v_mul_f32_e32 v67, 0.5, v114
	ds_bpermute_b32 v67, v119, v67
	v_fmac_f32_e32 v74, 0.5, v114
	v_cvt_pk_bf16_f32 v36, v89, v88
	v_cvt_pk_bf16_f32 v37, v91, v90
	v_mov_b32_e32 v46, v44
	s_waitcnt lgkmcnt(0)
	v_cndmask_b32_e32 v73, v67, v73, vcc
	v_add_f32_e32 v73, v74, v73
	v_mov_b32_e32 v74, v42
	v_mfma_f32_32x32x16_bf16 v[18:33], v[82:85], v[34:37], v[18:33]
	v_mov_b32_e32 v47, v45
	v_cvt_pk_bf16_f32 v38, v93, v92
	v_cvt_pk_bf16_f32 v39, v95, v94
	v_cvt_pk_bf16_f32 v40, v113, v112
	v_cvt_pk_bf16_f32 v41, v115, v114
	ds_write2_b32 v71, v53, v73 offset0:4 offset1:6
	v_add_u32_e32 v71, 32, v71
	v_mfma_f32_32x32x16_bf16 v[2:17], v[74:77], v[34:37], v[2:17]
	v_add_u32_e32 v72, 0x200, v72
	v_mfma_f32_32x32x16_bf16 v[2:17], v[46:49], v[38:41], v[2:17]
	v_mfma_f32_32x32x16_bf16 v[18:33], v[78:81], v[38:41], v[18:33]
	s_cbranch_scc0 .LBB0_189
	s_mov_b64 s[6:7], 0
